# P1/P7 prologues: compiler's full vmcnt(0) drain between K-tile 0 and K-tile 1 issue removed (only LDS-DMA loads in flight; the template's counted waits retire them)
# baseline (speedup 1.0000x reference)
.LBB0_306:
	s_nop 0
	v_bfe_u32 v144, v18, 4, 2
	v_and_b32_e32 v1, 15, v18
	v_lshlrev_b32_e32 v19, 4, v144
	v_lshlrev_b32_e32 v18, 2, v18
	s_and_b32 s19, s16, 3
	v_lshl_or_b32 v19, v1, 6, v19
	s_lshl_b32 s16, s22, 13
	v_and_b32_e32 v18, 32, v18
	s_add_i32 m0, s45, 0x18000
	v_lshl_add_u64 v[10:11], v[10:11], 0, s[96:97]
	s_lshl_b32 s49, s22, 6
	v_bitop3_b32 v20, v19, s16, v18 bitop3:0xde
	s_lshl_b32 s50, s19, 5
	s_lshl_b32 s16, s19, 12
	global_load_lds_dwordx4 v[10:11], off
	v_lshl_add_u64 v[8:9], v[8:9], 0, s[96:97]
	s_add_i32 m0, s45, 0x1a000
	s_add_i32 s51, s45, 0x8000
	s_add_i32 s52, s45, 0xa000
	v_bitop3_b32 v145, v19, s16, v18 bitop3:0xde
	global_load_lds_dwordx4 v[8:9], off
	v_lshl_add_u64 v[4:5], v[4:5], 0, s[96:97]
	s_mov_b32 m0, s51
	s_add_u32 s16, s30, 0x40080
	global_load_lds_dwordx4 v[4:5], off
	v_lshl_add_u64 v[4:5], v[6:7], 0, s[96:97]
	s_mov_b32 m0, s52
	s_addc_u32 s17, s31, 0
	global_load_lds_dwordx4 v[4:5], off
	s_add_i32 m0, s45, 0x1c000
	v_lshl_add_u64 v[4:5], s[16:17], 0, v[2:3]
	global_load_lds_dwordx4 v[4:5], off
	v_lshl_add_u64 v[4:5], s[16:17], 0, v[132:133]
	s_add_i32 m0, s45, 0x1e000
	s_cmpk_lt_u32 s18, 0x100
	global_load_lds_dwordx4 v[4:5], off
	v_lshlrev_b32_e32 v4, 14, v16
	v_and_b32_e32 v4, 0xffff8000, v4
	s_cselect_b64 s[16:17], -1, 0
	s_and_b32 s18, s18, 0xffffff00
	s_lshl_b32 s19, s19, 6
	v_lshl_add_u32 v4, v15, 11, v4
	v_and_b32_e32 v5, 1, v16
	s_or_b32 s53, s19, s18
	v_lshl_or_b32 v4, v5, 6, v4
	s_add_u32 s18, s6, 0x380000
	v_lshl_add_u32 v138, v17, 1, v4
	v_lshlrev_b32_e32 v4, 14, v12
	s_addc_u32 s19, s7, 0
	v_and_b32_e32 v4, 0xffff8000, v4
	s_waitcnt vmcnt(8)
	s_barrier
	s_waitcnt vmcnt(6)
	s_add_u32 s20, s6, 0x4700000
	v_lshl_add_u32 v4, v13, 11, v4
	v_and_b32_e32 v5, 1, v12
	s_addc_u32 s21, s7, 0
	s_lshl_b32 s54, s22, 8
	v_lshl_or_b32 v4, v5, 6, v4
	v_readlane_b32 s22, v253, 60
	s_add_i32 s54, s54, 0x20000
	v_mov_b32_e32 v139, v3
	v_lshl_add_u32 v140, v14, 1, v4
	v_mov_b32_e32 v141, v3
	s_mov_b32 s55, 0
	v_add_u32_e32 v146, 0, v20
	v_readlane_b32 s56, v253, 57
	s_mov_b32 s57, s22
	s_barrier
	v_readlane_b32 s23, v253, 61
	s_branch .LBB0_309

.LBB0_742:
	s_lshl_b32 s26, s48, 4
	s_ashr_i32 s27, s26, 31
	s_lshl_b64 s[26:27], s[26:27], 2
	s_nop 0
	v_bfe_u32 v156, v17, 4, 2
	s_waitcnt lgkmcnt(0)
	s_add_u32 s44, s22, s26
	v_and_b32_e32 v1, 15, v17
	v_lshlrev_b32_e32 v18, 4, v156
	v_lshlrev_b32_e32 v17, 2, v17
	s_addc_u32 s45, s23, s27
	s_and_b32 s15, s25, 3
	v_lshl_or_b32 v18, v1, 6, v18
	s_lshl_b32 s17, s34, 13
	v_and_b32_e32 v17, 32, v17
	s_add_i32 m0, s36, 0x18000
	v_lshl_add_u64 v[10:11], v[10:11], 0, s[96:97]
	s_lshl_b32 s66, s34, 6
	v_bitop3_b32 v19, v18, s17, v17 bitop3:0xde
	s_lshl_b32 s17, s15, 5
	s_lshl_b32 s22, s15, 12
	global_load_lds_dwordx4 v[10:11], off
	v_lshl_add_u64 v[8:9], v[8:9], 0, s[96:97]
	s_add_i32 m0, s36, 0x1a000
	s_add_i32 s67, s36, 0x8000
	s_add_i32 s68, s36, 0xa000
	v_bitop3_b32 v157, v18, s22, v17 bitop3:0xde
	global_load_lds_dwordx4 v[8:9], off
	v_lshl_add_u64 v[4:5], v[4:5], 0, s[96:97]
	s_mov_b32 m0, s67
	s_add_u32 s22, s20, 0x40080
	global_load_lds_dwordx4 v[4:5], off
	v_lshl_add_u64 v[4:5], v[6:7], 0, s[96:97]
	s_mov_b32 m0, s68
	s_addc_u32 s23, s21, 0
	global_load_lds_dwordx4 v[4:5], off
	s_add_i32 m0, s36, 0x1c000
	v_lshl_add_u64 v[4:5], s[22:23], 0, v[134:135]
	global_load_lds_dwordx4 v[4:5], off
	v_lshl_add_u64 v[4:5], s[22:23], 0, v[138:139]
	s_add_i32 m0, s36, 0x1e000
	s_cmpk_lt_u32 s24, 0x100
	global_load_lds_dwordx4 v[4:5], off
	s_mov_b32 s88, s48
	s_cselect_b64 s[46:47], -1, 0
	s_add_u32 s48, s6, 0x4c0000
	v_lshlrev_b32_e32 v4, 14, v2
	s_addc_u32 s49, s7, 0
	s_and_b32 s22, s24, 0xffffff00
	s_lshl_b32 s23, s15, 6
	v_and_b32_e32 v4, 0xffff8000, v4
	s_or_b32 s69, s23, s22
	v_lshl_add_u32 v4, v12, 11, v4
	v_and_b32_e32 v2, 1, v2
	s_add_u32 s50, s6, 0x100000
	v_lshl_or_b32 v2, v2, 6, v4
	s_addc_u32 s51, s7, 0
	s_lshl_b32 s70, s34, 8
	v_lshl_add_u32 v140, v13, 1, v2
	v_lshlrev_b32_e32 v2, 14, v14
	s_add_i32 s70, s70, 0x20000
	s_lshl_b32 s71, s15, 3
	v_and_b32_e32 v2, 0xffff8000, v2
	s_waitcnt vmcnt(8)
	s_barrier
	s_waitcnt vmcnt(6)
	s_cmp_eq_u32 s15, 0
	v_lshl_add_u32 v2, v15, 11, v2
	v_and_b32_e32 v4, 1, v14
	s_cselect_b64 s[52:53], -1, 0
	s_add_u32 s73, s6, 0xb0a0000
	v_lshl_or_b32 v2, v4, 6, v2
	s_mov_b32 s72, 0
	s_addc_u32 s74, s7, 0
	s_or_b32 s75, s71, 1
	s_or_b32 s76, s71, 2
	s_or_b32 s77, s71, 3
	s_or_b32 s78, s71, 4
	s_or_b32 s79, s71, 5
	s_or_b32 s80, s71, 6
	s_or_b32 s81, s71, 7
	v_mov_b32_e32 v141, v3
	v_lshl_add_u32 v142, v16, 1, v2
	v_mov_b32_e32 v143, v3
	v_add_u32_e32 v158, 0, v19
	s_lshl_b32 s82, s17, 1
	s_barrier
	s_mov_b32 s100, 0
	s_branch .LBB0_745
